# lambda dot products lane-parallel (one load round trip instead of 32), census counter loads issued together
# baseline (speedup 1.0000x reference)
; __device__ __forceinline__ unsigned xb_ld(unsigned* p)              { return __hip_atomic_load(p, __ATOMIC_RELAXED, __HIP_MEMORY_SCOPE_AGENT); }
; __device__ __forceinline__ void xcd_barrier_complete(unsigned* bar, unsigned x, unsigned& nloc, unsigned& nx) {
;     ...
;     for (;;) {
;         sum = 0u; cnt = 0u; mine = 0u;
; #pragma unroll
;         for (unsigned j = 0; j < 16; ++j) { const unsigned c = xb_ld(&bar[XB_XCNT(j)]); sum += c; cnt += (c > 0u) ? 1u : 0u; mine = (j == x) ? c : mine; }
;         if (sum == G) break;
;         __builtin_amdgcn_s_sleep(1);
;         if ((++sp & 255u) == 0u) { if (xb_ld(&bar[XB_TMO])) break; if (sp > XB_SPIN_CAP) { atomicAdd(&bar[XB_TMO], 1u); break; } }
;     }
.LBB0_129:
	v_readlane_b32 s14, v252, 59
	v_readlane_b32 s15, v252, 60
	s_mov_b64 s[20:21], -1
	s_waitcnt lgkmcnt(0)
	s_nop 3
	global_load_dword v0, v1, s[14:15] sc1
	global_load_dword v2, v1, s[14:15] offset:256 sc1
	global_load_dword v3, v1, s[14:15] offset:512 sc1
	global_load_dword v4, v1, s[14:15] offset:768 sc1
	global_load_dword v5, v1, s[14:15] offset:1024 sc1
	global_load_dword v6, v1, s[14:15] offset:1280 sc1
	global_load_dword v7, v1, s[14:15] offset:1536 sc1
	global_load_dword v8, v1, s[14:15] offset:1792 sc1
	global_load_dword v9, v1, s[14:15] offset:2048 sc1
	global_load_dword v10, v1, s[14:15] offset:2304 sc1
	global_load_dword v11, v1, s[14:15] offset:2560 sc1
	global_load_dword v12, v1, s[14:15] offset:2816 sc1
	global_load_dword v13, v1, s[14:15] offset:3072 sc1
	global_load_dword v14, v1, s[14:15] offset:3328 sc1
	global_load_dword v15, v1, s[14:15] offset:3584 sc1
	global_load_dword v16, v1, s[14:15] offset:3840 sc1
	s_mov_b64 s[14:15], -1
	s_waitcnt vmcnt(0)
	v_add_u32_e32 v17, v2, v0
	v_add_u32_e32 v17, v17, v3
	v_add_u32_e32 v17, v17, v4
	v_add_u32_e32 v17, v17, v5
	v_add_u32_e32 v17, v17, v6
	v_add_u32_e32 v17, v17, v7
	v_add_u32_e32 v17, v17, v8
	v_add_u32_e32 v17, v17, v9
	v_add_u32_e32 v17, v17, v10
	v_add_u32_e32 v17, v17, v11
	v_add_u32_e32 v17, v17, v12
	v_add_u32_e32 v17, v17, v13
	v_add_u32_e32 v17, v17, v14
	v_add_u32_e32 v17, v17, v15
	v_add_u32_e32 v17, v17, v16
	v_cmp_eq_u32_e32 vcc, s6, v17
	s_cbranch_vccnz .LBB0_128
	s_and_b32 s3, s2, 0xff
	s_cmp_eq_u32 s3, 0
	s_mov_b64 s[28:29], -1
	s_sleep 1
	s_cbranch_scc0 .LBB0_133
	v_readlane_b32 s14, v252, 57
	v_readlane_b32 s15, v252, 58
	s_nop 4
	global_load_dword v17, v1, s[14:15] sc1
	s_waitcnt vmcnt(0)
	v_cmp_eq_u32_e32 vcc, 0, v17
	s_cbranch_vccnz .LBB0_135
	s_mov_b64 s[28:29], 0
	s_mov_b64 s[14:15], -1

; __global__ void __launch_bounds__(512) hymba_fwd(Params p) {
;     ...
;             float d1 = 0.f, d2 = 0.f, mq = 0.f, mk = 0.f;
;             for (int j = 0; j < 64; ++j) { d1 += p.in[6][l * 64 + j] * p.in[7][l * 64 + j]; d2 += p.in[8][l * 64 + j] * p.in[9][l * 64 + j];
;                 mq = fmaxf(mq, fabsf(p.in[4][l * 64 + j])); mk = fmaxf(mk, fabsf(p.in[5][l * 64 + j])); }
.LBB0_559:
	v_and_b32_e32 v6, 63, v212
	v_lshlrev_b32_e32 v6, 2, v6
	global_load_dword v7, v6, s[2:3]
	s_mov_b32 s30, s6
	s_mov_b32 s31, s10
	global_load_dword v8, v6, s[30:31]
	s_mov_b32 s30, s11
	s_mov_b32 s31, s14
	global_load_dword v9, v6, s[30:31]
	s_mov_b32 s30, s15
	s_mov_b32 s31, s20
	global_load_dword v10, v6, s[30:31]
	global_load_dword v11, v6, s[58:59]
	global_load_dword v12, v6, s[60:61]
	s_waitcnt vmcnt(0)
	v_mul_f32_e32 v2, v7, v8
	v_mul_f32_e32 v3, v9, v10
	v_and_b32_e32 v5, 0x7fffffff, v11
	v_and_b32_e32 v4, 0x7fffffff, v12
	s_nop 1
	v_add_f32_dpp v2, v2, v2 quad_perm:[1,0,3,2] row_mask:0xf bank_mask:0xf
	v_add_f32_dpp v3, v3, v3 quad_perm:[1,0,3,2] row_mask:0xf bank_mask:0xf
	v_max_f32_dpp v5, v5, v5 quad_perm:[1,0,3,2] row_mask:0xf bank_mask:0xf
	v_max_f32_dpp v4, v4, v4 quad_perm:[1,0,3,2] row_mask:0xf bank_mask:0xf
	v_add_f32_dpp v2, v2, v2 quad_perm:[2,3,0,1] row_mask:0xf bank_mask:0xf
	v_add_f32_dpp v3, v3, v3 quad_perm:[2,3,0,1] row_mask:0xf bank_mask:0xf
	v_max_f32_dpp v5, v5, v5 quad_perm:[2,3,0,1] row_mask:0xf bank_mask:0xf
	v_max_f32_dpp v4, v4, v4 quad_perm:[2,3,0,1] row_mask:0xf bank_mask:0xf
	v_add_f32_dpp v2, v2, v2 row_half_mirror row_mask:0xf bank_mask:0xf
	v_add_f32_dpp v3, v3, v3 row_half_mirror row_mask:0xf bank_mask:0xf
	v_max_f32_dpp v5, v5, v5 row_half_mirror row_mask:0xf bank_mask:0xf
	v_max_f32_dpp v4, v4, v4 row_half_mirror row_mask:0xf bank_mask:0xf
	v_add_f32_dpp v2, v2, v2 row_mirror row_mask:0xf bank_mask:0xf
	v_add_f32_dpp v3, v3, v3 row_mirror row_mask:0xf bank_mask:0xf
	v_max_f32_dpp v5, v5, v5 row_mirror row_mask:0xf bank_mask:0xf
	v_max_f32_dpp v4, v4, v4 row_mirror row_mask:0xf bank_mask:0xf
	s_nop 1
	v_readlane_b32 s6, v2, 0
	v_readlane_b32 s10, v2, 16
	v_readlane_b32 s11, v2, 32
	v_readlane_b32 s14, v2, 48
	s_nop 1
	v_mov_b32_e32 v2, s6
	v_add_f32_e32 v2, s10, v2
	v_add_f32_e32 v2, s11, v2
	v_add_f32_e32 v2, s14, v2
	v_readlane_b32 s6, v3, 0
	v_readlane_b32 s10, v3, 16
	v_readlane_b32 s11, v3, 32
	v_readlane_b32 s14, v3, 48
	s_nop 1
	v_mov_b32_e32 v3, s6
	v_add_f32_e32 v3, s10, v3
	v_add_f32_e32 v3, s11, v3
	v_add_f32_e32 v3, s14, v3
	v_readlane_b32 s6, v5, 0
	v_readlane_b32 s10, v5, 16
	v_readlane_b32 s11, v5, 32
	v_readlane_b32 s14, v5, 48
	s_nop 1
	v_mov_b32_e32 v5, s6
	v_max_f32_e32 v5, s10, v5
	v_max_f32_e32 v5, s11, v5
	v_max_f32_e32 v5, s14, v5
	v_readlane_b32 s6, v4, 0
	v_readlane_b32 s10, v4, 16
	v_readlane_b32 s11, v4, 32
	v_readlane_b32 s14, v4, 48
	s_nop 1
	v_mov_b32_e32 v4, s6
	v_max_f32_e32 v4, s10, v4
	v_max_f32_e32 v4, s11, v4
	v_max_f32_e32 v4, s14, v4
	s_add_u32 s8, s24, s40
	v_mov_b32_e32 v193, v212
	s_addc_u32 s9, s25, s41
	s_getreg_b32 s2, hwreg(HW_REG_XCC_ID, 0, 4)
	v_readfirstlane_b32 s30, v193
	v_mov_b32_e32 v221, 0
	v_cmp_eq_u32_e64 s[36:37], 0, v193
	s_and_saveexec_b64 s[10:11], s[36:37]
	s_cbranch_execz .LBB0_568
	v_mov_b32_e32 v221, 0
	s_mov_b64 s[14:15], 0
	s_mov_b32 s3, 0
	s_branch .LBB0_564
